# code placement: every hot K-loop head at 32 mod 64 bytes
# baseline (speedup 1.0000x reference)
.LBB0_180:
	s_add_i32 s85, s85, 1
	s_cmp_lt_i32 s85, s43
	s_cselect_b64 s[8:9], -1, 0
	s_cmp_eq_u32 s85, s43
	s_cselect_b64 s[26:27], -1, 0
	s_min_i32 s35, s85, s43
	s_mov_b32 s34, s70
	s_waitcnt lgkmcnt(0)
	s_mul_i32 s35, s35, s92
	v_readlane_b32 s70, v253, 44
	s_add_i32 s35, s35, s70
	s_min_i32 s35, s35, 0x40f
	s_ashr_i32 s70, s35, 31
	s_lshr_b32 s70, s70, 29
	s_add_i32 s70, s35, s70
	s_mov_b64 s[4:5], s[74:75]
	s_ashr_i32 s74, s70, 3
	s_and_b32 s70, s70, -8
	s_and_b64 s[26:27], s[26:27], s[68:69]
	s_sub_i32 s35, s35, s70
	s_cmp_lt_i32 s35, 0
	s_cselect_b32 s70, s45, 0x82
	s_mul_i32 s35, s35, s70
	s_add_i32 s35, s35, s74
	s_mul_hi_i32 s70, s35, 0xd20d20d3
	s_add_i32 s70, s70, s35
	s_lshr_b32 s74, s70, 31
	s_ashr_i32 s70, s70, 6
	s_add_i32 s70, s70, s74
	s_mov_b64 s[6:7], s[76:77]
	s_mul_i32 s76, s70, 3
	s_sub_i32 s74, 40, s76
	s_min_u32 s77, s74, 3
	s_mulk_i32 s70, 0x4e
	s_sub_i32 s86, s35, s70
	v_cvt_f32_ubyte0_e32 v1, s77
	v_cvt_f32_i32_e32 v0, s86
	v_rcp_iflag_f32_e32 v2, v1
	s_mov_b32 s35, s46
	s_ashr_i32 s46, s86, 30
	s_or_b32 s46, s46, 1
	v_mul_f32_e32 v2, v0, v2
	v_trunc_f32_e32 v2, v2
	v_fma_f32 v0, -v2, v1, v0
	v_cvt_i32_f32_e32 v2, v2
	v_cmp_ge_f32_e64 s[74:75], |v0|, v1
	s_and_b64 s[74:75], s[74:75], exec
	s_cselect_b32 s46, s46, 0
	v_readfirstlane_b32 s70, v2
	s_add_i32 s70, s70, s46
	s_mul_i32 s46, s70, s77
	s_sub_i32 s46, s86, s46
	s_sext_i32_i8 s46, s46
	s_add_i32 s46, s76, s46
	s_or_b64 s[92:93], s[8:9], s[26:27]
	s_lshl_b32 s8, s46, 8
	s_ashr_i32 s9, s8, 31
	s_lshl_b64 s[8:9], s[8:9], 12
	s_add_u32 s74, s36, s8
	s_addc_u32 s75, s37, s9
	s_and_b64 s[8:9], s[92:93], exec
	s_cselect_b32 s26, s75, s5
	s_cselect_b32 s27, s74, s4
	s_bfe_i64 s[8:9], s[70:71], 0x80000
	s_lshl_b64 s[8:9], s[8:9], 20
	s_add_u32 s76, s38, s8
	s_addc_u32 s77, s39, s9
	s_and_b64 s[8:9], s[92:93], exec
	s_cselect_b32 s86, s77, s7
	s_cselect_b32 s91, s76, s6
	s_add_u32 s4, s4, 0x80080
	s_addc_u32 s5, s5, 0
	s_add_u32 s94, s6, 0x100
	v_mov_b32_e32 v0, 0
	s_addc_u32 s95, s7, 0
	s_mov_b32 s96, -2
	v_mov_b32_e32 v1, v0
	v_mov_b32_e32 v2, v0
	v_mov_b32_e32 v3, v0
	v_mov_b32_e32 v4, v0
	v_mov_b32_e32 v5, v0
	v_mov_b32_e32 v6, v0
	v_mov_b32_e32 v7, v0
	v_mov_b32_e32 v16, v0
	v_mov_b32_e32 v17, v0
	v_mov_b32_e32 v18, v0
	v_mov_b32_e32 v19, v0
	v_mov_b32_e32 v20, v0
	v_mov_b32_e32 v21, v0
	v_mov_b32_e32 v22, v0
	v_mov_b32_e32 v23, v0
	v_mov_b32_e32 v32, v0
	v_mov_b32_e32 v33, v0
	v_mov_b32_e32 v34, v0
	v_mov_b32_e32 v35, v0
	v_mov_b32_e32 v36, v0
	v_mov_b32_e32 v37, v0
	v_mov_b32_e32 v38, v0
	v_mov_b32_e32 v39, v0
	v_mov_b32_e32 v48, v0
	v_mov_b32_e32 v49, v0
	v_mov_b32_e32 v50, v0
	v_mov_b32_e32 v51, v0
	v_mov_b32_e32 v52, v0
	v_mov_b32_e32 v53, v0
	v_mov_b32_e32 v54, v0
	v_mov_b32_e32 v55, v0
	v_mov_b32_e32 v8, v0
	v_mov_b32_e32 v9, v0
	v_mov_b32_e32 v10, v0
	v_mov_b32_e32 v11, v0
	v_mov_b32_e32 v12, v0
	v_mov_b32_e32 v13, v0
	v_mov_b32_e32 v14, v0
	v_mov_b32_e32 v15, v0
	v_mov_b32_e32 v24, v0
	v_mov_b32_e32 v25, v0
	v_mov_b32_e32 v26, v0
	v_mov_b32_e32 v27, v0
	v_mov_b32_e32 v28, v0
	v_mov_b32_e32 v29, v0
	v_mov_b32_e32 v30, v0
	v_mov_b32_e32 v31, v0
	v_mov_b32_e32 v40, v0
	v_mov_b32_e32 v41, v0
	v_mov_b32_e32 v42, v0
	v_mov_b32_e32 v43, v0
	v_mov_b32_e32 v44, v0
	v_mov_b32_e32 v45, v0
	v_mov_b32_e32 v46, v0
	v_mov_b32_e32 v47, v0
	v_mov_b32_e32 v56, v0
	v_mov_b32_e32 v57, v0
	v_mov_b32_e32 v58, v0
	v_mov_b32_e32 v59, v0
	v_mov_b32_e32 v60, v0
	v_mov_b32_e32 v61, v0
	v_mov_b32_e32 v62, v0
	v_mov_b32_e32 v63, v0
	v_mov_b32_e32 v64, v0
	v_mov_b32_e32 v65, v0
	v_mov_b32_e32 v66, v0
	v_mov_b32_e32 v67, v0
	v_mov_b32_e32 v68, v0
	v_mov_b32_e32 v69, v0
	v_mov_b32_e32 v70, v0
	v_mov_b32_e32 v71, v0
	v_mov_b32_e32 v80, v0
	v_mov_b32_e32 v81, v0
	v_mov_b32_e32 v82, v0
	v_mov_b32_e32 v83, v0
	v_mov_b32_e32 v84, v0
	v_mov_b32_e32 v85, v0
	v_mov_b32_e32 v86, v0
	v_mov_b32_e32 v87, v0
	v_mov_b32_e32 v96, v0
	v_mov_b32_e32 v97, v0
	v_mov_b32_e32 v98, v0
	v_mov_b32_e32 v99, v0
	v_mov_b32_e32 v100, v0
	v_mov_b32_e32 v101, v0
	v_mov_b32_e32 v102, v0
	v_mov_b32_e32 v103, v0
	v_mov_b32_e32 v112, v0
	v_mov_b32_e32 v113, v0
	v_mov_b32_e32 v114, v0
	v_mov_b32_e32 v115, v0
	v_mov_b32_e32 v116, v0
	v_mov_b32_e32 v117, v0
	v_mov_b32_e32 v118, v0
	v_mov_b32_e32 v119, v0
	v_mov_b32_e32 v72, v0
	v_mov_b32_e32 v73, v0
	v_mov_b32_e32 v74, v0
	v_mov_b32_e32 v75, v0
	v_mov_b32_e32 v76, v0
	v_mov_b32_e32 v77, v0
	v_mov_b32_e32 v78, v0
	v_mov_b32_e32 v79, v0
	v_mov_b32_e32 v88, v0
	v_mov_b32_e32 v89, v0
	v_mov_b32_e32 v90, v0
	v_mov_b32_e32 v91, v0
	v_mov_b32_e32 v92, v0
	v_mov_b32_e32 v93, v0
	v_mov_b32_e32 v94, v0
	v_mov_b32_e32 v95, v0
	v_mov_b32_e32 v104, v0
	v_mov_b32_e32 v105, v0
	v_mov_b32_e32 v106, v0
	v_mov_b32_e32 v107, v0
	v_mov_b32_e32 v108, v0
	v_mov_b32_e32 v109, v0
	v_mov_b32_e32 v110, v0
	v_mov_b32_e32 v111, v0
	v_mov_b32_e32 v120, v0
	v_mov_b32_e32 v121, v0
	v_mov_b32_e32 v122, v0
	v_mov_b32_e32 v123, v0
	v_mov_b32_e32 v124, v0
	v_mov_b32_e32 v125, v0
	v_mov_b32_e32 v126, v0
	v_mov_b32_e32 v127, v0
	s_nop 0
	s_nop 0
	s_nop 0
	s_nop 0
	s_nop 0
	s_nop 0
	s_nop 0
	s_nop 0
	s_nop 0
	s_nop 0
	s_nop 0
	s_nop 0
	s_nop 0
	s_nop 0
	s_nop 0
